# gate/up K loop: first-iteration segment waits of later units allow the previous unit's 8 epilogue stores to stay in flight (vmcnt 16)
# baseline (speedup 1.0000x reference)
.LBB0_812:
	s_add_u32 s38, s36, 0xfffc0080
	s_addc_u32 s39, s37, -1
	s_add_i32 s55, 0, 0x10000
	s_cmp_eq_u32 s54, 12
	s_cselect_b32 s41, s17, s39
	s_cselect_b32 s40, s50, s38
	v_add_u32_e32 v149, s55, v145
	s_cselect_b32 s39, s15, s53
	s_cselect_b32 s38, s51, s52
	s_add_i32 s58, 0, 0x14000
	ds_read_b128 v[140:143], v149
	ds_read_b128 v[150:153], v149 offset:1024
	ds_read_b128 v[164:167], v149 offset:2048
	ds_read_b128 v[168:171], v149 offset:3072
	v_add_u32_e32 v149, s58, v145
	ds_read_b128 v[176:179], v149
	ds_read_b128 v[180:183], v149 offset:1024
	ds_read_b128 v[184:187], v149 offset:2048
	ds_read_b128 v[212:215], v149 offset:3072
	v_lshl_add_u64 v[154:155], s[36:37], 0, v[136:137]
	s_add_i32 m0, s42, 0xc000
	ds_read_b128 v[216:219], v148
	ds_read_b128 v[220:223], v148 offset:1024
	ds_read_b128 v[224:227], v148 offset:2048
	ds_read_b128 v[228:231], v148 offset:3072
	ds_read_b128 v[232:235], v148 offset:4096
	ds_read_b128 v[236:239], v148 offset:5120
	ds_read_b128 v[240:243], v148 offset:6144
	ds_read_b128 v[244:247], v148 offset:7168
	global_load_lds_dwordx4 v[154:155], off
	v_lshl_add_u64 v[154:155], s[36:37], 0, v[138:139]
	s_add_i32 m0, s42, 0xe000
	s_nop 0
	global_load_lds_dwordx4 v[154:155], off
	s_cmp_eq_u32 s54, -2
	s_cselect_b32 s59, s49, 0
	s_cmp_lg_u32 s59, 0
	s_cbranch_scc1 .Lgu_loose0
	s_waitcnt vmcnt(8)
.Lgu_loose0:
	s_waitcnt vmcnt(16)
	s_waitcnt lgkmcnt(0)
	s_barrier
	s_setprio 1
	s_waitcnt lgkmcnt(0)
	v_mfma_f32_16x16x32_bf16 v[126:129], v[140:143], v[216:219], v[126:129]
	v_mfma_f32_16x16x32_bf16 v[118:121], v[164:167], v[216:219], v[118:121]
	v_mfma_f32_16x16x32_bf16 v[110:113], v[140:143], v[224:227], v[110:113]
	v_mfma_f32_16x16x32_bf16 v[102:105], v[164:167], v[224:227], v[102:105]
	v_mfma_f32_16x16x32_bf16 v[94:97], v[140:143], v[232:235], v[94:97]
	v_mfma_f32_16x16x32_bf16 v[86:89], v[164:167], v[232:235], v[86:89]
	v_mfma_f32_16x16x32_bf16 v[78:81], v[140:143], v[240:243], v[78:81]
	v_mfma_f32_16x16x32_bf16 v[70:73], v[164:167], v[240:243], v[70:73]
	v_mfma_f32_16x16x32_bf16 v[126:129], v[150:153], v[220:223], v[126:129]
	v_mfma_f32_16x16x32_bf16 v[118:121], v[168:171], v[220:223], v[118:121]
	v_mfma_f32_16x16x32_bf16 v[110:113], v[150:153], v[228:231], v[110:113]
	v_mfma_f32_16x16x32_bf16 v[102:105], v[168:171], v[228:231], v[102:105]
	v_mfma_f32_16x16x32_bf16 v[94:97], v[150:153], v[236:239], v[94:97]
	v_mfma_f32_16x16x32_bf16 v[86:89], v[168:171], v[236:239], v[86:89]
	v_mfma_f32_16x16x32_bf16 v[78:81], v[150:153], v[244:247], v[78:81]
	v_mfma_f32_16x16x32_bf16 v[70:73], v[168:171], v[244:247], v[70:73]
	s_setprio 0
	s_setprio 1
	v_mfma_f32_16x16x32_bf16 v[122:125], v[176:179], v[216:219], v[122:125]
	v_mfma_f32_16x16x32_bf16 v[114:117], v[184:187], v[216:219], v[114:117]
	v_mfma_f32_16x16x32_bf16 v[106:109], v[176:179], v[224:227], v[106:109]
	v_mfma_f32_16x16x32_bf16 v[98:101], v[184:187], v[224:227], v[98:101]
	v_mfma_f32_16x16x32_bf16 v[90:93], v[176:179], v[232:235], v[90:93]
	v_mfma_f32_16x16x32_bf16 v[82:85], v[184:187], v[232:235], v[82:85]
	v_mfma_f32_16x16x32_bf16 v[74:77], v[176:179], v[240:243], v[74:77]
	v_mfma_f32_16x16x32_bf16 v[66:69], v[184:187], v[240:243], v[66:69]
	v_mfma_f32_16x16x32_bf16 v[122:125], v[180:183], v[220:223], v[122:125]
	v_mfma_f32_16x16x32_bf16 v[114:117], v[212:215], v[220:223], v[114:117]
	v_mfma_f32_16x16x32_bf16 v[106:109], v[180:183], v[228:231], v[106:109]
	v_mfma_f32_16x16x32_bf16 v[98:101], v[212:215], v[228:231], v[98:101]
	v_mfma_f32_16x16x32_bf16 v[90:93], v[180:183], v[236:239], v[90:93]
	v_mfma_f32_16x16x32_bf16 v[82:85], v[212:215], v[236:239], v[82:85]
	v_mfma_f32_16x16x32_bf16 v[74:77], v[180:183], v[244:247], v[74:77]
	v_mfma_f32_16x16x32_bf16 v[66:69], v[212:215], v[244:247], v[66:69]
	s_setprio 0
	s_barrier
	s_add_i32 s55, s55, s7
	v_lshl_add_u64 v[154:155], s[38:39], 0, v[0:1]
	s_mov_b32 m0, s55
	ds_read_b128 v[216:219], v148 offset:16384
	ds_read_b128 v[220:223], v148 offset:17408
	ds_read_b128 v[224:227], v148 offset:18432
	ds_read_b128 v[228:231], v148 offset:19456
	ds_read_b128 v[232:235], v148 offset:20480
	ds_read_b128 v[236:239], v148 offset:21504
	ds_read_b128 v[240:243], v148 offset:22528
	ds_read_b128 v[244:247], v148 offset:23552
	global_load_lds_dwordx4 v[154:155], off
	s_add_i32 m0, s55, 0x2000
	s_add_u32 s56, s38, 0x40000
	v_lshl_add_u64 v[172:173], s[38:39], 0, v[134:135]
	s_addc_u32 s57, s39, 0
	s_add_i32 s55, s58, s7
	global_load_lds_dwordx4 v[172:173], off
	v_lshl_add_u64 v[248:249], s[56:57], 0, v[0:1]
	s_mov_b32 m0, s55
	v_lshl_add_u64 v[250:251], s[40:41], 0, v[132:133]
	global_load_lds_dwordx4 v[248:249], off
	v_lshl_add_u64 v[248:249], s[56:57], 0, v[134:135]
	s_add_i32 m0, s55, 0x2000
	s_nop 0
	global_load_lds_dwordx4 v[248:249], off
	v_lshl_add_u64 v[248:249], s[40:41], 0, v[130:131]
	s_mov_b32 m0, s42
	s_nop 0
	global_load_lds_dwordx4 v[248:249], off
	s_mov_b32 m0, s43
	s_nop 0
	global_load_lds_dwordx4 v[250:251], off
	s_cmp_eq_u32 s54, -2
	s_cselect_b32 s59, s49, 0
	s_cmp_lg_u32 s59, 0
	s_cbranch_scc1 .Lgu_loose1
	s_waitcnt vmcnt(8)
.Lgu_loose1:
	s_waitcnt vmcnt(16)
	s_waitcnt lgkmcnt(0)
	s_barrier
	s_setprio 1
	s_waitcnt lgkmcnt(0)
	v_mfma_f32_16x16x32_bf16 v[62:65], v[140:143], v[216:219], v[62:65]
	v_mfma_f32_16x16x32_bf16 v[54:57], v[164:167], v[216:219], v[54:57]
	v_mfma_f32_16x16x32_bf16 v[46:49], v[140:143], v[224:227], v[46:49]
	v_mfma_f32_16x16x32_bf16 v[38:41], v[164:167], v[224:227], v[38:41]
	v_mfma_f32_16x16x32_bf16 v[30:33], v[140:143], v[232:235], v[30:33]
	v_mfma_f32_16x16x32_bf16 v[22:25], v[164:167], v[232:235], v[22:25]
	v_mfma_f32_16x16x32_bf16 v[14:17], v[140:143], v[240:243], v[14:17]
	v_mfma_f32_16x16x32_bf16 v[6:9], v[164:167], v[240:243], v[6:9]
	v_mfma_f32_16x16x32_bf16 v[62:65], v[150:153], v[220:223], v[62:65]
	v_mfma_f32_16x16x32_bf16 v[54:57], v[168:171], v[220:223], v[54:57]
	v_mfma_f32_16x16x32_bf16 v[46:49], v[150:153], v[228:231], v[46:49]
	v_mfma_f32_16x16x32_bf16 v[38:41], v[168:171], v[228:231], v[38:41]
	v_mfma_f32_16x16x32_bf16 v[30:33], v[150:153], v[236:239], v[30:33]
	v_mfma_f32_16x16x32_bf16 v[22:25], v[168:171], v[236:239], v[22:25]
	v_mfma_f32_16x16x32_bf16 v[14:17], v[150:153], v[244:247], v[14:17]
	v_mfma_f32_16x16x32_bf16 v[6:9], v[168:171], v[244:247], v[6:9]
	s_setprio 0
	s_setprio 1
	v_mfma_f32_16x16x32_bf16 v[58:61], v[176:179], v[216:219], v[58:61]
	v_mfma_f32_16x16x32_bf16 v[50:53], v[184:187], v[216:219], v[50:53]
	v_mfma_f32_16x16x32_bf16 v[42:45], v[176:179], v[224:227], v[42:45]
	v_mfma_f32_16x16x32_bf16 v[34:37], v[184:187], v[224:227], v[34:37]
	v_mfma_f32_16x16x32_bf16 v[26:29], v[176:179], v[232:235], v[26:29]
	v_mfma_f32_16x16x32_bf16 v[18:21], v[184:187], v[232:235], v[18:21]
	v_mfma_f32_16x16x32_bf16 v[10:13], v[176:179], v[240:243], v[10:13]
	v_mfma_f32_16x16x32_bf16 v[2:5], v[184:187], v[240:243], v[2:5]
	v_mfma_f32_16x16x32_bf16 v[58:61], v[180:183], v[220:223], v[58:61]
	v_mfma_f32_16x16x32_bf16 v[50:53], v[212:215], v[220:223], v[50:53]
	v_mfma_f32_16x16x32_bf16 v[42:45], v[180:183], v[228:231], v[42:45]
	v_mfma_f32_16x16x32_bf16 v[34:37], v[212:215], v[228:231], v[34:37]
	v_mfma_f32_16x16x32_bf16 v[26:29], v[180:183], v[236:239], v[26:29]
	v_mfma_f32_16x16x32_bf16 v[18:21], v[212:215], v[236:239], v[18:21]
	v_mfma_f32_16x16x32_bf16 v[10:13], v[180:183], v[244:247], v[10:13]
	v_mfma_f32_16x16x32_bf16 v[2:5], v[212:215], v[244:247], v[2:5]
	s_setprio 0
	s_barrier
	s_add_i32 s55, 0, 0x18000
	v_add_u32_e32 v149, s55, v145
	s_add_i32 s56, 0, 0x1c000
	ds_read_b128 v[140:143], v149
	ds_read_b128 v[150:153], v149 offset:1024
	ds_read_b128 v[164:167], v149 offset:2048
	ds_read_b128 v[168:171], v149 offset:3072
	v_add_u32_e32 v149, s56, v145
	ds_read_b128 v[176:179], v149
	ds_read_b128 v[180:183], v149 offset:1024
	ds_read_b128 v[184:187], v149 offset:2048
	ds_read_b128 v[212:215], v149 offset:3072
	s_add_u32 s40, s40, 0x40000
	s_addc_u32 s41, s41, 0
	s_mov_b32 m0, s44
	v_lshl_add_u64 v[198:199], s[40:41], 0, v[130:131]
	ds_read_b128 v[216:219], v148 offset:32768
	ds_read_b128 v[220:223], v148 offset:33792
	ds_read_b128 v[224:227], v148 offset:34816
	ds_read_b128 v[228:231], v148 offset:35840
	ds_read_b128 v[232:235], v148 offset:36864
	ds_read_b128 v[236:239], v148 offset:37888
	ds_read_b128 v[240:243], v148 offset:38912
	ds_read_b128 v[244:247], v148 offset:39936
	global_load_lds_dwordx4 v[198:199], off
	v_lshl_add_u64 v[198:199], s[40:41], 0, v[132:133]
	s_mov_b32 m0, s45
	s_nop 0
	global_load_lds_dwordx4 v[198:199], off
	s_waitcnt vmcnt(8)
	s_waitcnt lgkmcnt(0)
	s_barrier
	s_setprio 1
	s_waitcnt lgkmcnt(0)
	v_mfma_f32_16x16x32_bf16 v[126:129], v[140:143], v[216:219], v[126:129]
	v_mfma_f32_16x16x32_bf16 v[118:121], v[164:167], v[216:219], v[118:121]
	v_mfma_f32_16x16x32_bf16 v[110:113], v[140:143], v[224:227], v[110:113]
	v_mfma_f32_16x16x32_bf16 v[102:105], v[164:167], v[224:227], v[102:105]
	v_mfma_f32_16x16x32_bf16 v[94:97], v[140:143], v[232:235], v[94:97]
	v_mfma_f32_16x16x32_bf16 v[86:89], v[164:167], v[232:235], v[86:89]
	v_mfma_f32_16x16x32_bf16 v[78:81], v[140:143], v[240:243], v[78:81]
	v_mfma_f32_16x16x32_bf16 v[70:73], v[164:167], v[240:243], v[70:73]
	v_mfma_f32_16x16x32_bf16 v[126:129], v[150:153], v[220:223], v[126:129]
	v_mfma_f32_16x16x32_bf16 v[118:121], v[168:171], v[220:223], v[118:121]
	v_mfma_f32_16x16x32_bf16 v[110:113], v[150:153], v[228:231], v[110:113]
	v_mfma_f32_16x16x32_bf16 v[102:105], v[168:171], v[228:231], v[102:105]
	v_mfma_f32_16x16x32_bf16 v[94:97], v[150:153], v[236:239], v[94:97]
	v_mfma_f32_16x16x32_bf16 v[86:89], v[168:171], v[236:239], v[86:89]
	v_mfma_f32_16x16x32_bf16 v[78:81], v[150:153], v[244:247], v[78:81]
	v_mfma_f32_16x16x32_bf16 v[70:73], v[168:171], v[244:247], v[70:73]
	s_setprio 0
	s_setprio 1
	v_mfma_f32_16x16x32_bf16 v[122:125], v[176:179], v[216:219], v[122:125]
	v_mfma_f32_16x16x32_bf16 v[114:117], v[184:187], v[216:219], v[114:117]
	v_mfma_f32_16x16x32_bf16 v[106:109], v[176:179], v[224:227], v[106:109]
	v_mfma_f32_16x16x32_bf16 v[98:101], v[184:187], v[224:227], v[98:101]
	v_mfma_f32_16x16x32_bf16 v[90:93], v[176:179], v[232:235], v[90:93]
	v_mfma_f32_16x16x32_bf16 v[82:85], v[184:187], v[232:235], v[82:85]
	v_mfma_f32_16x16x32_bf16 v[74:77], v[176:179], v[240:243], v[74:77]
	v_mfma_f32_16x16x32_bf16 v[66:69], v[184:187], v[240:243], v[66:69]
	v_mfma_f32_16x16x32_bf16 v[122:125], v[180:183], v[220:223], v[122:125]
	v_mfma_f32_16x16x32_bf16 v[114:117], v[212:215], v[220:223], v[114:117]
	v_mfma_f32_16x16x32_bf16 v[106:109], v[180:183], v[228:231], v[106:109]
	v_mfma_f32_16x16x32_bf16 v[98:101], v[212:215], v[228:231], v[98:101]
	v_mfma_f32_16x16x32_bf16 v[90:93], v[180:183], v[236:239], v[90:93]
	v_mfma_f32_16x16x32_bf16 v[82:85], v[212:215], v[236:239], v[82:85]
	v_mfma_f32_16x16x32_bf16 v[74:77], v[180:183], v[244:247], v[74:77]
	v_mfma_f32_16x16x32_bf16 v[66:69], v[212:215], v[244:247], v[66:69]
	s_setprio 0
	s_barrier
	s_add_i32 s40, s55, s7
	v_lshl_add_u64 v[154:155], v[154:155], 0, s[20:21]
	s_mov_b32 m0, s40
	ds_read_b128 v[216:219], v148 offset:49152
	ds_read_b128 v[220:223], v148 offset:50176
	ds_read_b128 v[224:227], v148 offset:51200
	ds_read_b128 v[228:231], v148 offset:52224
	ds_read_b128 v[232:235], v148 offset:53248
	ds_read_b128 v[236:239], v148 offset:54272
	ds_read_b128 v[240:243], v148 offset:55296
	ds_read_b128 v[244:247], v148 offset:56320
	global_load_lds_dwordx4 v[154:155], off
	s_add_i32 m0, s40, 0x2000
	s_add_u32 s38, s38, 0x40080
	v_lshl_add_u64 v[154:155], v[172:173], 0, s[20:21]
	s_addc_u32 s39, s39, 0
	s_add_i32 s40, s56, s7
	global_load_lds_dwordx4 v[154:155], off
	v_lshl_add_u64 v[154:155], s[38:39], 0, v[0:1]
	s_mov_b32 m0, s40
	s_nop 0
	global_load_lds_dwordx4 v[154:155], off
	v_lshl_add_u64 v[154:155], s[38:39], 0, v[134:135]
	s_add_i32 m0, s40, 0x2000
	s_nop 0
	global_load_lds_dwordx4 v[154:155], off
	v_lshl_add_u64 v[154:155], v[248:249], 0, s[20:21]
	s_mov_b32 m0, s46
	s_nop 0
	global_load_lds_dwordx4 v[154:155], off
	v_lshl_add_u64 v[154:155], v[250:251], 0, s[20:21]
	s_mov_b32 m0, s47
	s_nop 0
	global_load_lds_dwordx4 v[154:155], off
	s_waitcnt vmcnt(8)
	s_waitcnt lgkmcnt(0)
	s_barrier
	s_setprio 1
	s_waitcnt lgkmcnt(0)
	v_mfma_f32_16x16x32_bf16 v[62:65], v[140:143], v[216:219], v[62:65]
	v_mfma_f32_16x16x32_bf16 v[54:57], v[164:167], v[216:219], v[54:57]
	v_mfma_f32_16x16x32_bf16 v[46:49], v[140:143], v[224:227], v[46:49]
	v_mfma_f32_16x16x32_bf16 v[38:41], v[164:167], v[224:227], v[38:41]
	v_mfma_f32_16x16x32_bf16 v[30:33], v[140:143], v[232:235], v[30:33]
	v_mfma_f32_16x16x32_bf16 v[22:25], v[164:167], v[232:235], v[22:25]
	v_mfma_f32_16x16x32_bf16 v[14:17], v[140:143], v[240:243], v[14:17]
	v_mfma_f32_16x16x32_bf16 v[6:9], v[164:167], v[240:243], v[6:9]
	v_mfma_f32_16x16x32_bf16 v[62:65], v[150:153], v[220:223], v[62:65]
	v_mfma_f32_16x16x32_bf16 v[54:57], v[168:171], v[220:223], v[54:57]
	v_mfma_f32_16x16x32_bf16 v[46:49], v[150:153], v[228:231], v[46:49]
	v_mfma_f32_16x16x32_bf16 v[38:41], v[168:171], v[228:231], v[38:41]
	v_mfma_f32_16x16x32_bf16 v[30:33], v[150:153], v[236:239], v[30:33]
	v_mfma_f32_16x16x32_bf16 v[22:25], v[168:171], v[236:239], v[22:25]
	v_mfma_f32_16x16x32_bf16 v[14:17], v[150:153], v[244:247], v[14:17]
	v_mfma_f32_16x16x32_bf16 v[6:9], v[168:171], v[244:247], v[6:9]
	s_setprio 0
	s_setprio 1
	v_mfma_f32_16x16x32_bf16 v[58:61], v[176:179], v[216:219], v[58:61]
	v_mfma_f32_16x16x32_bf16 v[50:53], v[184:187], v[216:219], v[50:53]
	v_mfma_f32_16x16x32_bf16 v[42:45], v[176:179], v[224:227], v[42:45]
	v_mfma_f32_16x16x32_bf16 v[34:37], v[184:187], v[224:227], v[34:37]
	v_mfma_f32_16x16x32_bf16 v[26:29], v[176:179], v[232:235], v[26:29]
	v_mfma_f32_16x16x32_bf16 v[18:21], v[184:187], v[232:235], v[18:21]
	v_mfma_f32_16x16x32_bf16 v[10:13], v[176:179], v[240:243], v[10:13]
	v_mfma_f32_16x16x32_bf16 v[2:5], v[184:187], v[240:243], v[2:5]
	v_mfma_f32_16x16x32_bf16 v[58:61], v[180:183], v[220:223], v[58:61]
	v_mfma_f32_16x16x32_bf16 v[50:53], v[212:215], v[220:223], v[50:53]
	v_mfma_f32_16x16x32_bf16 v[42:45], v[180:183], v[228:231], v[42:45]
	v_mfma_f32_16x16x32_bf16 v[34:37], v[212:215], v[228:231], v[34:37]
	v_mfma_f32_16x16x32_bf16 v[26:29], v[180:183], v[236:239], v[26:29]
	v_mfma_f32_16x16x32_bf16 v[18:21], v[212:215], v[236:239], v[18:21]
	v_mfma_f32_16x16x32_bf16 v[10:13], v[180:183], v[244:247], v[10:13]
	v_mfma_f32_16x16x32_bf16 v[2:5], v[212:215], v[244:247], v[2:5]
	s_setprio 0
	s_barrier
	s_add_i32 s54, s54, 2
	s_add_u32 s36, s36, 0x100
	s_addc_u32 s37, s37, 0
	s_add_u32 s52, s52, 0x100
	s_addc_u32 s53, s53, 0
	s_cmp_gt_u32 s54, 13
	s_cbranch_scc0 .LBB0_812
	s_and_b64 vcc, exec, s[12:13]
	s_cbranch_vccz .LBB0_815
	s_barrier
